# same batching of the gain loads for the transpose instances ahead of the GEMM units in P1 and P4 (two batches of 16, v238-253)
# baseline (speedup 1.0000x reference)
; #define LAS __attribute__((address_space(3)))
; __device__ __forceinline__ void tr_load(const TrItem& t, float (&v)[32], int lane) {
;     const int n = lane & 31, kh = lane >> 5; const float* wp = t.W + (size_t)(t.k0 + kh) * t.ldw + t.n0 + (n < t.nvalid ? n : 0);
; #pragma unroll
;     for (int i = 0; i < 32; ++i) v[i] = wp[(size_t)(2 * i) * t.ldw];
; }
; __device__ __forceinline__ void tr_finish(const TrItem& t, const float (&v)[32], LAS float* scr, int lane) {
;     const int n = lane & 31, kh = lane >> 5;
; #pragma unroll
;     for (int i = 0; i < 32; ++i) { float x = n < t.nvalid ? v[i] : 0.f; if (t.g) x *= t.g[t.k0 + 2 * i + kh]; scr[(2 * i + kh) * 33 + n] = x; }
.LBB0_311:
	v_add_u32_e32 v6, s80, v1
	v_ashrrev_i32_e32 v7, 31, v6
	v_mul_lo_u32 v2, s76, v7
	v_mul_lo_u32 v5, s77, v6
	s_waitcnt vmcnt(41)
	v_mad_u64_u32 v[40:41], s[0:1], s76, v6, 0
	v_add3_u32 v41, v41, v2, v5
	v_lshl_add_u64 v[40:41], v[40:41], 2, s[4:5]
	s_ashr_i32 s7, s6, 31
	v_cndmask_b32_e64 v2, 0, v0, s[84:85]
	v_lshl_add_u64 v[40:41], s[6:7], 2, v[40:41]
	v_lshlrev_b32_e32 v2, 2, v2
	v_lshl_add_u64 v[40:41], v[40:41], 0, v[2:3]
	s_lshl_b64 s[0:1], s[76:77], 3
	v_lshl_add_u64 v[64:65], v[40:41], 0, s[0:1]
	v_lshl_add_u64 v[66:67], v[64:65], 0, s[0:1]
	v_lshl_add_u64 v[68:69], v[66:67], 0, s[0:1]
	v_lshl_add_u64 v[70:71], v[68:69], 0, s[0:1]
	v_lshl_add_u64 v[78:79], v[70:71], 0, s[0:1]
	v_lshl_add_u64 v[80:81], v[78:79], 0, s[0:1]
	v_lshl_add_u64 v[82:83], v[80:81], 0, s[0:1]
	global_load_dword v77, v[40:41], off
	global_load_dword v76, v[64:65], off
	global_load_dword v75, v[66:67], off
	global_load_dword v74, v[68:69], off
	global_load_dword v73, v[70:71], off
	global_load_dword v72, v[78:79], off
	s_nop 0
	global_load_dword v71, v[80:81], off
	global_load_dword v70, v[82:83], off
	v_lshl_add_u64 v[40:41], v[82:83], 0, s[0:1]
	global_load_dword v69, v[40:41], off
	v_lshl_add_u64 v[40:41], v[40:41], 0, s[0:1]
	global_load_dword v68, v[40:41], off
	v_lshl_add_u64 v[40:41], v[40:41], 0, s[0:1]
	global_load_dword v67, v[40:41], off
	v_lshl_add_u64 v[40:41], v[40:41], 0, s[0:1]
	global_load_dword v66, v[40:41], off
	v_lshl_add_u64 v[40:41], v[40:41], 0, s[0:1]
	global_load_dword v65, v[40:41], off
	v_lshl_add_u64 v[40:41], v[40:41], 0, s[0:1]
	global_load_dword v64, v[40:41], off
	v_lshl_add_u64 v[40:41], v[40:41], 0, s[0:1]
	global_load_dword v62, v[40:41], off
	v_lshl_add_u64 v[40:41], v[40:41], 0, s[0:1]
	global_load_dword v60, v[40:41], off
	v_lshl_add_u64 v[40:41], v[40:41], 0, s[0:1]
	global_load_dword v58, v[40:41], off
	v_lshl_add_u64 v[40:41], v[40:41], 0, s[0:1]
	global_load_dword v56, v[40:41], off
	v_lshl_add_u64 v[40:41], v[40:41], 0, s[0:1]
	global_load_dword v55, v[40:41], off
	v_lshl_add_u64 v[40:41], v[40:41], 0, s[0:1]
	global_load_dword v53, v[40:41], off
	v_lshl_add_u64 v[40:41], v[40:41], 0, s[0:1]
	global_load_dword v51, v[40:41], off
	v_lshl_add_u64 v[40:41], v[40:41], 0, s[0:1]
	global_load_dword v49, v[40:41], off
	v_lshl_add_u64 v[40:41], v[40:41], 0, s[0:1]
	global_load_dword v47, v[40:41], off
	v_lshl_add_u64 v[40:41], v[40:41], 0, s[0:1]
	global_load_dword v45, v[40:41], off
	v_lshl_add_u64 v[40:41], v[40:41], 0, s[0:1]
	v_lshl_add_u64 v[78:79], v[40:41], 0, s[0:1]
	global_load_dword v43, v[40:41], off
	s_nop 0
	global_load_dword v41, v[78:79], off
	v_lshl_add_u64 v[78:79], v[78:79], 0, s[0:1]
	global_load_dword v40, v[78:79], off
	v_lshl_add_u64 v[78:79], v[78:79], 0, s[0:1]
	global_load_dword v38, v[78:79], off
	v_lshl_add_u64 v[78:79], v[78:79], 0, s[0:1]
	global_load_dword v36, v[78:79], off
	v_lshl_add_u64 v[78:79], v[78:79], 0, s[0:1]
	global_load_dword v34, v[78:79], off
	v_lshl_add_u64 v[78:79], v[78:79], 0, s[0:1]
	global_load_dword v32, v[78:79], off
	v_lshl_add_u64 v[78:79], v[78:79], 0, s[0:1]
	global_load_dword v30, v[78:79], off
	s_cmp_lg_u64 s[54:55], 0
	v_add_u32_e32 v8, s92, v1
	v_cmp_gt_u32_e64 s[6:7], s73, v0
	s_cselect_b64 s[0:1], -1, 0
	s_cmp_eq_u64 s[54:55], 0
	s_waitcnt vmcnt(62)
	v_cndmask_b32_e64 v2, 0, v9, s[6:7]
	v_ashrrev_i32_e32 v9, 31, v8
	s_cbranch_scc1 .LBB0_313
	v_lshl_add_u64 v[78:79], v[8:9], 2, s[54:55]
	global_load_dword v238, v[78:79], off
	global_load_dword v239, v[78:79], off offset:8
	global_load_dword v240, v[78:79], off offset:16
	global_load_dword v241, v[78:79], off offset:24
	global_load_dword v242, v[78:79], off offset:32
	global_load_dword v243, v[78:79], off offset:40
	global_load_dword v244, v[78:79], off offset:48
	global_load_dword v245, v[78:79], off offset:56
	global_load_dword v246, v[78:79], off offset:64
	global_load_dword v247, v[78:79], off offset:72
	global_load_dword v248, v[78:79], off offset:80
	global_load_dword v249, v[78:79], off offset:88
	global_load_dword v250, v[78:79], off offset:96
	global_load_dword v251, v[78:79], off offset:104
	global_load_dword v252, v[78:79], off offset:112
	global_load_dword v253, v[78:79], off offset:120
	s_waitcnt vmcnt(0)
	v_mul_f32_e32 v2, v2, v238
.LBB0_313:
	ds_write_b32 v14, v2
	v_cndmask_b32_e64 v2, 0, 1, s[0:1]
	v_cmp_ne_u32_e64 s[4:5], 1, v2
	s_andn2_b64 vcc, exec, s[0:1]
	v_cndmask_b32_e64 v2, 0, v63, s[6:7]
	s_cbranch_vccnz .LBB0_315
	v_lshl_add_u64 v[78:79], v[8:9], 2, s[54:55]
	v_mul_f32_e32 v2, v2, v239
.LBB0_315:
	ds_write_b32 v14, v2 offset:264
	s_and_b64 vcc, exec, s[4:5]
	s_waitcnt vmcnt(61)
	v_cndmask_b32_e64 v2, 0, v61, s[6:7]
	s_cbranch_vccnz .LBB0_317
	v_lshl_add_u64 v[78:79], v[8:9], 2, s[54:55]
	v_mul_f32_e32 v2, v2, v240
.LBB0_317:
	ds_write_b32 v14, v2 offset:528
	s_and_b64 vcc, exec, s[4:5]
	s_waitcnt vmcnt(60)
	v_cndmask_b32_e64 v2, 0, v59, s[6:7]
	s_cbranch_vccnz .LBB0_319
	v_lshl_add_u64 v[78:79], v[8:9], 2, s[54:55]
	v_mul_f32_e32 v2, v2, v241
.LBB0_319:
	ds_write_b32 v14, v2 offset:792
	s_and_b64 vcc, exec, s[4:5]
	s_waitcnt vmcnt(59)
	v_cndmask_b32_e64 v2, 0, v57, s[6:7]
	s_cbranch_vccnz .LBB0_321
	v_lshl_add_u64 v[78:79], v[8:9], 2, s[54:55]
	v_mul_f32_e32 v2, v2, v242
.LBB0_321:
	ds_write_b32 v14, v2 offset:1056
	s_and_b64 vcc, exec, s[4:5]
	s_waitcnt vmcnt(58)
	v_cndmask_b32_e64 v2, 0, v54, s[6:7]
	s_cbranch_vccnz .LBB0_323
	v_lshl_add_u64 v[78:79], v[8:9], 2, s[54:55]
	v_mul_f32_e32 v2, v2, v243
.LBB0_323:
	ds_write_b32 v14, v2 offset:1320
	s_and_b64 vcc, exec, s[4:5]
	s_waitcnt vmcnt(57)
	v_cndmask_b32_e64 v2, 0, v52, s[6:7]
	s_cbranch_vccnz .LBB0_325
	v_lshl_add_u64 v[78:79], v[8:9], 2, s[54:55]
	v_mul_f32_e32 v2, v2, v244
; #define LAS __attribute__((address_space(3)))
; __device__ __forceinline__ void tr_finish(const TrItem& t, const float (&v)[32], LAS float* scr, int lane) {
;     const int n = lane & 31, kh = lane >> 5;
; #pragma unroll
;     for (int i = 0; i < 32; ++i) { float x = n < t.nvalid ? v[i] : 0.f; if (t.g) x *= t.g[t.k0 + 2 * i + kh]; scr[(2 * i + kh) * 33 + n] = x; }
.LBB0_325:
	ds_write_b32 v14, v2 offset:1584
	s_and_b64 vcc, exec, s[4:5]
	s_waitcnt vmcnt(56)
	v_cndmask_b32_e64 v2, 0, v50, s[6:7]
	s_cbranch_vccnz .LBB0_327
	v_lshl_add_u64 v[78:79], v[8:9], 2, s[54:55]
	v_mul_f32_e32 v2, v2, v245
.LBB0_327:
	ds_write_b32 v14, v2 offset:1848
	s_and_b64 vcc, exec, s[4:5]
	s_waitcnt vmcnt(55)
	v_cndmask_b32_e64 v2, 0, v48, s[6:7]
	s_cbranch_vccnz .LBB0_329
	v_lshl_add_u64 v[78:79], v[8:9], 2, s[54:55]
	v_mul_f32_e32 v2, v2, v246
.LBB0_329:
	ds_write_b32 v14, v2 offset:2112
	s_and_b64 vcc, exec, s[4:5]
	s_waitcnt vmcnt(54)
	v_cndmask_b32_e64 v2, 0, v46, s[6:7]
	s_cbranch_vccnz .LBB0_331
	v_lshl_add_u64 v[78:79], v[8:9], 2, s[54:55]
	v_mul_f32_e32 v2, v2, v247
.LBB0_331:
	ds_write_b32 v14, v2 offset:2376
	s_and_b64 vcc, exec, s[4:5]
	s_waitcnt vmcnt(53)
	v_cndmask_b32_e64 v2, 0, v44, s[6:7]
	s_cbranch_vccnz .LBB0_333
	v_lshl_add_u64 v[78:79], v[8:9], 2, s[54:55]
	v_mul_f32_e32 v2, v2, v248
.LBB0_333:
	ds_write_b32 v14, v2 offset:2640
	s_and_b64 vcc, exec, s[4:5]
	s_waitcnt vmcnt(52)
	v_cndmask_b32_e64 v2, 0, v42, s[6:7]
	s_cbranch_vccnz .LBB0_335
	v_lshl_add_u64 v[78:79], v[8:9], 2, s[54:55]
	v_mul_f32_e32 v2, v2, v249
.LBB0_335:
	ds_write_b32 v14, v2 offset:2904
	s_and_b64 vcc, exec, s[4:5]
	s_waitcnt vmcnt(51)
	v_cndmask_b32_e64 v2, 0, v39, s[6:7]
	s_cbranch_vccnz .LBB0_337
	v_lshl_add_u64 v[78:79], v[8:9], 2, s[54:55]
	v_mul_f32_e32 v2, v2, v250
.LBB0_337:
	ds_write_b32 v14, v2 offset:3168
	s_and_b64 vcc, exec, s[4:5]
	s_waitcnt vmcnt(50)
	v_cndmask_b32_e64 v2, 0, v37, s[6:7]
	s_cbranch_vccnz .LBB0_339
	v_lshl_add_u64 v[78:79], v[8:9], 2, s[54:55]
	v_mul_f32_e32 v2, v2, v251
.LBB0_339:
	ds_write_b32 v14, v2 offset:3432
	s_and_b64 vcc, exec, s[4:5]
	s_waitcnt vmcnt(49)
	v_cndmask_b32_e64 v2, 0, v35, s[6:7]
	s_cbranch_vccnz .LBB0_341
	v_lshl_add_u64 v[78:79], v[8:9], 2, s[54:55]
	v_mul_f32_e32 v2, v2, v252
.LBB0_341:
	ds_write_b32 v14, v2 offset:3696
	s_and_b64 vcc, exec, s[4:5]
	s_waitcnt vmcnt(48)
	v_cndmask_b32_e64 v2, 0, v33, s[6:7]
	s_cbranch_vccnz .LBB0_343
	v_lshl_add_u64 v[78:79], v[8:9], 2, s[54:55]
	v_mul_f32_e32 v2, v2, v253
.LBB0_343:
	ds_write_b32 v14, v2 offset:3960
	s_and_b64 vcc, exec, s[4:5]
	s_waitcnt vmcnt(47)
	v_cndmask_b32_e64 v2, 0, v31, s[6:7]
	s_cbranch_vccnz .LBB0_345
	v_lshl_add_u64 v[78:79], v[8:9], 2, s[54:55]
	global_load_dword v238, v[78:79], off offset:128
	global_load_dword v239, v[78:79], off offset:136
	global_load_dword v240, v[78:79], off offset:144
	global_load_dword v241, v[78:79], off offset:152
	global_load_dword v242, v[78:79], off offset:160
	global_load_dword v243, v[78:79], off offset:168
	global_load_dword v244, v[78:79], off offset:176
	global_load_dword v245, v[78:79], off offset:184
	global_load_dword v246, v[78:79], off offset:192
	global_load_dword v247, v[78:79], off offset:200
	global_load_dword v248, v[78:79], off offset:208
	global_load_dword v249, v[78:79], off offset:216
	global_load_dword v250, v[78:79], off offset:224
	global_load_dword v251, v[78:79], off offset:232
	global_load_dword v252, v[78:79], off offset:240
	global_load_dword v253, v[78:79], off offset:248
	s_waitcnt vmcnt(0)
	v_mul_f32_e32 v2, v2, v238
.LBB0_345:
	ds_write_b32 v14, v2 offset:4224
	s_and_b64 vcc, exec, s[4:5]
	s_waitcnt vmcnt(46)
	v_cndmask_b32_e64 v2, 0, v29, s[6:7]
	s_cbranch_vccnz .LBB0_347
	v_lshl_add_u64 v[78:79], v[8:9], 2, s[54:55]
	v_mul_f32_e32 v2, v2, v239
.LBB0_347:
	ds_write_b32 v14, v2 offset:4488
	s_and_b64 vcc, exec, s[4:5]
	s_waitcnt vmcnt(45)
	v_cndmask_b32_e64 v2, 0, v28, s[6:7]
	s_cbranch_vccnz .LBB0_349
	v_lshl_add_u64 v[28:29], v[8:9], 2, s[54:55]
	v_mul_f32_e32 v2, v2, v240
.LBB0_349:
	ds_write_b32 v14, v2 offset:4752
	s_and_b64 vcc, exec, s[4:5]
	s_waitcnt vmcnt(44)
	v_cndmask_b32_e64 v2, 0, v27, s[6:7]
	s_cbranch_vccnz .LBB0_351
	v_lshl_add_u64 v[28:29], v[8:9], 2, s[54:55]
	v_mul_f32_e32 v2, v2, v241
.LBB0_351:
	ds_write_b32 v14, v2 offset:5016
	s_and_b64 vcc, exec, s[4:5]
	s_waitcnt vmcnt(43)
	v_cndmask_b32_e64 v2, 0, v26, s[6:7]
	s_cbranch_vccnz .LBB0_353
	v_lshl_add_u64 v[26:27], v[8:9], 2, s[54:55]
	v_mul_f32_e32 v2, v2, v242
.LBB0_353:
	ds_write_b32 v14, v2 offset:5280
	s_and_b64 vcc, exec, s[4:5]
	s_waitcnt vmcnt(42)
	v_cndmask_b32_e64 v2, 0, v25, s[6:7]
	s_cbranch_vccnz .LBB0_355
	v_lshl_add_u64 v[26:27], v[8:9], 2, s[54:55]
	v_mul_f32_e32 v2, v2, v243
.LBB0_355:
	ds_write_b32 v14, v2 offset:5544
	s_and_b64 vcc, exec, s[4:5]
	s_waitcnt vmcnt(41)
	v_cndmask_b32_e64 v2, 0, v24, s[6:7]
	s_cbranch_vccnz .LBB0_357
	v_lshl_add_u64 v[24:25], v[8:9], 2, s[54:55]
	v_mul_f32_e32 v2, v2, v244
.LBB0_357:
	ds_write_b32 v14, v2 offset:5808
	s_and_b64 vcc, exec, s[4:5]
	s_waitcnt vmcnt(40)
	v_cndmask_b32_e64 v2, 0, v23, s[6:7]
	s_cbranch_vccnz .LBB0_359
	v_lshl_add_u64 v[24:25], v[8:9], 2, s[54:55]
	v_mul_f32_e32 v2, v2, v245
.LBB0_359:
	ds_write_b32 v14, v2 offset:6072
	s_and_b64 vcc, exec, s[4:5]
	s_waitcnt vmcnt(39)
	v_cndmask_b32_e64 v2, 0, v22, s[6:7]
	s_cbranch_vccnz .LBB0_361
	v_lshl_add_u64 v[22:23], v[8:9], 2, s[54:55]
	v_mul_f32_e32 v2, v2, v246
.LBB0_361:
	ds_write_b32 v14, v2 offset:6336
	s_and_b64 vcc, exec, s[4:5]
	s_waitcnt vmcnt(38)
	v_cndmask_b32_e64 v2, 0, v21, s[6:7]
	s_cbranch_vccnz .LBB0_363
	v_lshl_add_u64 v[22:23], v[8:9], 2, s[54:55]
	v_mul_f32_e32 v2, v2, v247
.LBB0_363:
	ds_write_b32 v14, v2 offset:6600
	s_and_b64 vcc, exec, s[4:5]
	s_waitcnt vmcnt(37)
	v_cndmask_b32_e64 v2, 0, v20, s[6:7]
	s_cbranch_vccnz .LBB0_365
	v_lshl_add_u64 v[20:21], v[8:9], 2, s[54:55]
	v_mul_f32_e32 v2, v2, v248
.LBB0_365:
	ds_write_b32 v14, v2 offset:6864
	s_and_b64 vcc, exec, s[4:5]
	s_waitcnt vmcnt(36)
	v_cndmask_b32_e64 v2, 0, v19, s[6:7]
	s_cbranch_vccnz .LBB0_367
	v_lshl_add_u64 v[20:21], v[8:9], 2, s[54:55]
	v_mul_f32_e32 v2, v2, v249
.LBB0_367:
	ds_write_b32 v14, v2 offset:7128
	s_and_b64 vcc, exec, s[4:5]
	s_waitcnt vmcnt(35)
	v_cndmask_b32_e64 v2, 0, v18, s[6:7]
	s_cbranch_vccnz .LBB0_369
	v_lshl_add_u64 v[18:19], v[8:9], 2, s[54:55]
	v_mul_f32_e32 v2, v2, v250
.LBB0_369:
	ds_write_b32 v14, v2 offset:7392
	s_and_b64 vcc, exec, s[4:5]
	s_waitcnt vmcnt(34)
	v_cndmask_b32_e64 v2, 0, v17, s[6:7]
	s_cbranch_vccnz .LBB0_371
	v_lshl_add_u64 v[18:19], v[8:9], 2, s[54:55]
	v_mul_f32_e32 v2, v2, v251
.LBB0_371:
	ds_write_b32 v14, v2 offset:7656
	s_and_b64 vcc, exec, s[4:5]
	s_waitcnt vmcnt(33)
	v_cndmask_b32_e64 v2, 0, v16, s[6:7]
	s_cbranch_vccnz .LBB0_373
	v_lshl_add_u64 v[16:17], v[8:9], 2, s[54:55]
	v_mul_f32_e32 v2, v2, v252
.LBB0_373:
	ds_write_b32 v14, v2 offset:7920
	s_and_b64 vcc, exec, s[4:5]
	s_waitcnt vmcnt(32)
	v_cndmask_b32_e64 v2, 0, v15, s[6:7]
	s_cbranch_vccnz .LBB0_375
	v_lshl_add_u64 v[8:9], v[8:9], 2, s[54:55]
	v_mul_f32_e32 v2, v2, v253

; #define LAS __attribute__((address_space(3)))
; __device__ __forceinline__ void tr_load(const TrItem& t, float (&v)[32], int lane) {
;     const int n = lane & 31, kh = lane >> 5; const float* wp = t.W + (size_t)(t.k0 + kh) * t.ldw + t.n0 + (n < t.nvalid ? n : 0);
; #pragma unroll
;     for (int i = 0; i < 32; ++i) v[i] = wp[(size_t)(2 * i) * t.ldw];
; }
; __device__ __forceinline__ void tr_finish(const TrItem& t, const float (&v)[32], LAS float* scr, int lane) {
;     const int n = lane & 31, kh = lane >> 5;
; #pragma unroll
;     for (int i = 0; i < 32; ++i) { float x = n < t.nvalid ? v[i] : 0.f; if (t.g) x *= t.g[t.k0 + 2 * i + kh]; scr[(2 * i + kh) * 33 + n] = x; }
.LBB0_401:
	v_add_u32_e32 v2, s92, v1
	v_ashrrev_i32_e32 v5, 31, v2
	v_mul_lo_u32 v5, s74, v5
	v_mul_lo_u32 v15, s75, v2
	v_mad_u64_u32 v[8:9], s[0:1], s74, v2, 0
	v_add3_u32 v9, v9, v5, v15
	v_cmp_gt_u32_e32 vcc, s73, v0
	v_lshl_add_u64 v[8:9], v[8:9], 2, s[4:5]
	s_ashr_i32 s7, s6, 31
	v_cndmask_b32_e32 v2, 0, v0, vcc
	v_lshl_add_u64 v[8:9], s[6:7], 2, v[8:9]
	v_lshlrev_b32_e32 v2, 2, v2
	v_lshl_add_u64 v[8:9], v[8:9], 0, v[2:3]
	s_lshl_b64 s[0:1], s[74:75], 3
	v_lshl_add_u64 v[16:17], v[8:9], 0, s[0:1]
	v_lshl_add_u64 v[18:19], v[16:17], 0, s[0:1]
	v_lshl_add_u64 v[20:21], v[18:19], 0, s[0:1]
	v_lshl_add_u64 v[22:23], v[20:21], 0, s[0:1]
	v_lshl_add_u64 v[24:25], v[22:23], 0, s[0:1]
	v_lshl_add_u64 v[26:27], v[24:25], 0, s[0:1]
	v_lshl_add_u64 v[28:29], v[26:27], 0, s[0:1]
	global_load_dword v9, v[8:9], off
	s_nop 0
	global_load_dword v63, v[16:17], off
	global_load_dword v61, v[18:19], off
	global_load_dword v59, v[20:21], off
	global_load_dword v57, v[22:23], off
	global_load_dword v54, v[24:25], off
	global_load_dword v52, v[26:27], off
	global_load_dword v50, v[28:29], off
	v_lshl_add_u64 v[16:17], v[28:29], 0, s[0:1]
	global_load_dword v48, v[16:17], off
	v_lshl_add_u64 v[16:17], v[16:17], 0, s[0:1]
	global_load_dword v46, v[16:17], off
	v_lshl_add_u64 v[16:17], v[16:17], 0, s[0:1]
	global_load_dword v44, v[16:17], off
	v_lshl_add_u64 v[16:17], v[16:17], 0, s[0:1]
	global_load_dword v42, v[16:17], off
	v_lshl_add_u64 v[16:17], v[16:17], 0, s[0:1]
	global_load_dword v39, v[16:17], off
	v_lshl_add_u64 v[16:17], v[16:17], 0, s[0:1]
	global_load_dword v37, v[16:17], off
	v_lshl_add_u64 v[16:17], v[16:17], 0, s[0:1]
	global_load_dword v35, v[16:17], off
	v_lshl_add_u64 v[16:17], v[16:17], 0, s[0:1]
	global_load_dword v33, v[16:17], off
	v_lshl_add_u64 v[16:17], v[16:17], 0, s[0:1]
	global_load_dword v31, v[16:17], off
	v_lshl_add_u64 v[16:17], v[16:17], 0, s[0:1]
	global_load_dword v29, v[16:17], off
	v_lshl_add_u64 v[16:17], v[16:17], 0, s[0:1]
	global_load_dword v28, v[16:17], off
	v_lshl_add_u64 v[16:17], v[16:17], 0, s[0:1]
	global_load_dword v27, v[16:17], off
	v_lshl_add_u64 v[16:17], v[16:17], 0, s[0:1]
	global_load_dword v26, v[16:17], off
	v_lshl_add_u64 v[16:17], v[16:17], 0, s[0:1]
	global_load_dword v25, v[16:17], off
	v_lshl_add_u64 v[16:17], v[16:17], 0, s[0:1]
	global_load_dword v24, v[16:17], off
	v_lshl_add_u64 v[16:17], v[16:17], 0, s[0:1]
	global_load_dword v23, v[16:17], off
	v_lshl_add_u64 v[16:17], v[16:17], 0, s[0:1]
	global_load_dword v22, v[16:17], off
	v_lshl_add_u64 v[16:17], v[16:17], 0, s[0:1]
	global_load_dword v21, v[16:17], off
	v_lshl_add_u64 v[16:17], v[16:17], 0, s[0:1]
	global_load_dword v20, v[16:17], off
	v_lshl_add_u64 v[16:17], v[16:17], 0, s[0:1]
	global_load_dword v19, v[16:17], off
	v_lshl_add_u64 v[16:17], v[16:17], 0, s[0:1]
	v_lshl_add_u64 v[78:79], v[16:17], 0, s[0:1]
	global_load_dword v18, v[16:17], off
	s_nop 0
	global_load_dword v17, v[78:79], off
	v_lshl_add_u64 v[78:79], v[78:79], 0, s[0:1]
	global_load_dword v16, v[78:79], off
	v_lshl_add_u64 v[78:79], v[78:79], 0, s[0:1]
	global_load_dword v15, v[78:79], off
	s_andn2_b64 vcc, exec, s[88:89]
	s_cbranch_vccnz .LBB0_284
	s_cmp_lg_u64 s[90:91], 0
	s_cselect_b64 s[0:1], -1, 0
	s_cmp_eq_u64 s[90:91], 0
	s_waitcnt vmcnt(62)
	v_cndmask_b32_e64 v2, 0, v77, s[84:85]
	v_lshl_add_u64 v[6:7], v[6:7], 2, s[90:91]
	s_cbranch_scc1 .LBB0_404
	global_load_dword v238, v[6:7], off
	global_load_dword v239, v[6:7], off offset:8
	global_load_dword v240, v[6:7], off offset:16
	global_load_dword v241, v[6:7], off offset:24
	global_load_dword v242, v[6:7], off offset:32
	global_load_dword v243, v[6:7], off offset:40
	global_load_dword v244, v[6:7], off offset:48
	global_load_dword v245, v[6:7], off offset:56
	global_load_dword v246, v[6:7], off offset:64
	global_load_dword v247, v[6:7], off offset:72
	global_load_dword v248, v[6:7], off offset:80
	global_load_dword v249, v[6:7], off offset:88
	global_load_dword v250, v[6:7], off offset:96
	global_load_dword v251, v[6:7], off offset:104
	global_load_dword v252, v[6:7], off offset:112
	global_load_dword v253, v[6:7], off offset:120
	s_waitcnt vmcnt(0)
	v_mul_f32_e32 v2, v2, v238
.LBB0_404:
	ds_write_b32 v14, v2
	v_cndmask_b32_e64 v2, 0, 1, s[0:1]
	v_cmp_ne_u32_e64 s[4:5], 1, v2
	s_andn2_b64 vcc, exec, s[0:1]
	v_cndmask_b32_e64 v2, 0, v76, s[84:85]
	s_cbranch_vccnz .LBB0_406
	v_mul_f32_e32 v2, v2, v239
.LBB0_406:
	ds_write_b32 v14, v2 offset:264
	s_and_b64 vcc, exec, s[4:5]
	v_cndmask_b32_e64 v2, 0, v75, s[84:85]
	s_cbranch_vccnz .LBB0_408
	v_mul_f32_e32 v2, v2, v240
.LBB0_408:
	ds_write_b32 v14, v2 offset:528
	s_and_b64 vcc, exec, s[4:5]
	v_cndmask_b32_e64 v2, 0, v74, s[84:85]
	s_cbranch_vccnz .LBB0_410
	v_mul_f32_e32 v2, v2, v241
.LBB0_410:
	ds_write_b32 v14, v2 offset:792
	s_and_b64 vcc, exec, s[4:5]
	v_cndmask_b32_e64 v2, 0, v73, s[84:85]
	s_cbranch_vccnz .LBB0_412
	v_mul_f32_e32 v2, v2, v242
.LBB0_412:
	ds_write_b32 v14, v2 offset:1056
	s_and_b64 vcc, exec, s[4:5]
	v_cndmask_b32_e64 v2, 0, v72, s[84:85]
	s_cbranch_vccnz .LBB0_414
	v_mul_f32_e32 v2, v2, v243
.LBB0_414:
	ds_write_b32 v14, v2 offset:1320
	s_and_b64 vcc, exec, s[4:5]
	s_waitcnt vmcnt(61)
	v_cndmask_b32_e64 v2, 0, v71, s[84:85]
	s_cbranch_vccnz .LBB0_416
	v_mul_f32_e32 v2, v2, v244
.LBB0_416:
	ds_write_b32 v14, v2 offset:1584
	s_and_b64 vcc, exec, s[4:5]
	s_waitcnt vmcnt(60)
	v_cndmask_b32_e64 v2, 0, v70, s[84:85]
	s_cbranch_vccnz .LBB0_418
	v_mul_f32_e32 v2, v2, v245
; #define LAS __attribute__((address_space(3)))
; __device__ __forceinline__ void tr_finish(const TrItem& t, const float (&v)[32], LAS float* scr, int lane) {
;     const int n = lane & 31, kh = lane >> 5;
; #pragma unroll
;     for (int i = 0; i < 32; ++i) { float x = n < t.nvalid ? v[i] : 0.f; if (t.g) x *= t.g[t.k0 + 2 * i + kh]; scr[(2 * i + kh) * 33 + n] = x; }
.LBB0_418:
	ds_write_b32 v14, v2 offset:1848
	s_and_b64 vcc, exec, s[4:5]
	s_waitcnt vmcnt(59)
	v_cndmask_b32_e64 v2, 0, v69, s[84:85]
	s_cbranch_vccnz .LBB0_420
	v_mul_f32_e32 v2, v2, v246
.LBB0_420:
	ds_write_b32 v14, v2 offset:2112
	s_and_b64 vcc, exec, s[4:5]
	s_waitcnt vmcnt(58)
	v_cndmask_b32_e64 v2, 0, v68, s[84:85]
	s_cbranch_vccnz .LBB0_422
	v_mul_f32_e32 v2, v2, v247
.LBB0_422:
	ds_write_b32 v14, v2 offset:2376
	s_and_b64 vcc, exec, s[4:5]
	s_waitcnt vmcnt(57)
	v_cndmask_b32_e64 v2, 0, v67, s[84:85]
	s_cbranch_vccnz .LBB0_424
	v_mul_f32_e32 v2, v2, v248
.LBB0_424:
	ds_write_b32 v14, v2 offset:2640
	s_and_b64 vcc, exec, s[4:5]
	s_waitcnt vmcnt(56)
	v_cndmask_b32_e64 v2, 0, v66, s[84:85]
	s_cbranch_vccnz .LBB0_426
	v_mul_f32_e32 v2, v2, v249
.LBB0_426:
	ds_write_b32 v14, v2 offset:2904
	s_and_b64 vcc, exec, s[4:5]
	s_waitcnt vmcnt(55)
	v_cndmask_b32_e64 v2, 0, v65, s[84:85]
	s_cbranch_vccnz .LBB0_428
	v_mul_f32_e32 v2, v2, v250
.LBB0_428:
	ds_write_b32 v14, v2 offset:3168
	s_and_b64 vcc, exec, s[4:5]
	s_waitcnt vmcnt(54)
	v_cndmask_b32_e64 v2, 0, v64, s[84:85]
	s_cbranch_vccnz .LBB0_430
	v_mul_f32_e32 v2, v2, v251
.LBB0_430:
	ds_write_b32 v14, v2 offset:3432
	s_and_b64 vcc, exec, s[4:5]
	s_waitcnt vmcnt(53)
	v_cndmask_b32_e64 v2, 0, v62, s[84:85]
	s_cbranch_vccnz .LBB0_432
	v_mul_f32_e32 v2, v2, v252
.LBB0_432:
	ds_write_b32 v14, v2 offset:3696
	s_and_b64 vcc, exec, s[4:5]
	s_waitcnt vmcnt(52)
	v_cndmask_b32_e64 v2, 0, v60, s[84:85]
	s_cbranch_vccnz .LBB0_434
	v_mul_f32_e32 v2, v2, v253
.LBB0_434:
	ds_write_b32 v14, v2 offset:3960
	s_and_b64 vcc, exec, s[4:5]
	s_waitcnt vmcnt(51)
	v_cndmask_b32_e64 v2, 0, v58, s[84:85]
	s_cbranch_vccnz .LBB0_436
	global_load_dword v238, v[6:7], off offset:128
	global_load_dword v239, v[6:7], off offset:136
	global_load_dword v240, v[6:7], off offset:144
	global_load_dword v241, v[6:7], off offset:152
	global_load_dword v242, v[6:7], off offset:160
	global_load_dword v243, v[6:7], off offset:168
	global_load_dword v244, v[6:7], off offset:176
	global_load_dword v245, v[6:7], off offset:184
	global_load_dword v246, v[6:7], off offset:192
	global_load_dword v247, v[6:7], off offset:200
	global_load_dword v248, v[6:7], off offset:208
	global_load_dword v249, v[6:7], off offset:216
	global_load_dword v250, v[6:7], off offset:224
	global_load_dword v251, v[6:7], off offset:232
	global_load_dword v252, v[6:7], off offset:240
	global_load_dword v253, v[6:7], off offset:248
	s_waitcnt vmcnt(0)
	v_mul_f32_e32 v2, v2, v238
.LBB0_436:
	ds_write_b32 v14, v2 offset:4224
	s_and_b64 vcc, exec, s[4:5]
	s_waitcnt vmcnt(50)
	v_cndmask_b32_e64 v2, 0, v56, s[84:85]
	s_cbranch_vccnz .LBB0_438
	v_mul_f32_e32 v2, v2, v239
.LBB0_438:
	ds_write_b32 v14, v2 offset:4488
	s_and_b64 vcc, exec, s[4:5]
	s_waitcnt vmcnt(49)
	v_cndmask_b32_e64 v2, 0, v55, s[84:85]
	s_cbranch_vccnz .LBB0_440
	v_mul_f32_e32 v2, v2, v240
.LBB0_440:
	ds_write_b32 v14, v2 offset:4752
	s_and_b64 vcc, exec, s[4:5]
	s_waitcnt vmcnt(48)
	v_cndmask_b32_e64 v2, 0, v53, s[84:85]
	s_cbranch_vccnz .LBB0_442
	v_mul_f32_e32 v2, v2, v241
.LBB0_442:
	ds_write_b32 v14, v2 offset:5016
	s_and_b64 vcc, exec, s[4:5]
	s_waitcnt vmcnt(47)
	v_cndmask_b32_e64 v2, 0, v51, s[84:85]
	s_cbranch_vccnz .LBB0_444
	v_mul_f32_e32 v2, v2, v242
.LBB0_444:
	ds_write_b32 v14, v2 offset:5280
	s_and_b64 vcc, exec, s[4:5]
	s_waitcnt vmcnt(46)
	v_cndmask_b32_e64 v2, 0, v49, s[84:85]
	s_cbranch_vccnz .LBB0_446
	v_mul_f32_e32 v2, v2, v243
.LBB0_446:
	ds_write_b32 v14, v2 offset:5544
	s_and_b64 vcc, exec, s[4:5]
	s_waitcnt vmcnt(45)
	v_cndmask_b32_e64 v2, 0, v47, s[84:85]
	s_cbranch_vccnz .LBB0_448
	v_mul_f32_e32 v2, v2, v244
.LBB0_448:
	ds_write_b32 v14, v2 offset:5808
	s_and_b64 vcc, exec, s[4:5]
	s_waitcnt vmcnt(44)
	v_cndmask_b32_e64 v2, 0, v45, s[84:85]
	s_cbranch_vccnz .LBB0_450
	v_mul_f32_e32 v2, v2, v245
.LBB0_450:
	ds_write_b32 v14, v2 offset:6072
	s_and_b64 vcc, exec, s[4:5]
	s_waitcnt vmcnt(43)
	v_cndmask_b32_e64 v2, 0, v43, s[84:85]
	s_cbranch_vccnz .LBB0_452
	v_mul_f32_e32 v2, v2, v246
.LBB0_452:
	ds_write_b32 v14, v2 offset:6336
	s_and_b64 vcc, exec, s[4:5]
	s_waitcnt vmcnt(42)
	v_cndmask_b32_e64 v2, 0, v41, s[84:85]
	s_cbranch_vccnz .LBB0_454
	v_mul_f32_e32 v2, v2, v247
.LBB0_454:
	ds_write_b32 v14, v2 offset:6600
	s_and_b64 vcc, exec, s[4:5]
	s_waitcnt vmcnt(41)
	v_cndmask_b32_e64 v2, 0, v40, s[84:85]
	s_cbranch_vccnz .LBB0_456
	v_mul_f32_e32 v2, v2, v248
.LBB0_456:
	ds_write_b32 v14, v2 offset:6864
	s_and_b64 vcc, exec, s[4:5]
	s_waitcnt vmcnt(40)
	v_cndmask_b32_e64 v2, 0, v38, s[84:85]
	s_cbranch_vccnz .LBB0_458
	v_mul_f32_e32 v2, v2, v249
.LBB0_458:
	ds_write_b32 v14, v2 offset:7128
	s_and_b64 vcc, exec, s[4:5]
	s_waitcnt vmcnt(39)
	v_cndmask_b32_e64 v2, 0, v36, s[84:85]
	s_cbranch_vccnz .LBB0_460
	v_mul_f32_e32 v2, v2, v250
.LBB0_460:
	ds_write_b32 v14, v2 offset:7392
	s_and_b64 vcc, exec, s[4:5]
	s_waitcnt vmcnt(38)
	v_cndmask_b32_e64 v2, 0, v34, s[84:85]
	s_cbranch_vccnz .LBB0_462
	v_mul_f32_e32 v2, v2, v251
.LBB0_462:
	ds_write_b32 v14, v2 offset:7656
	s_and_b64 vcc, exec, s[4:5]
	s_waitcnt vmcnt(37)
	v_cndmask_b32_e64 v2, 0, v32, s[84:85]
	s_cbranch_vccnz .LBB0_464
	v_mul_f32_e32 v2, v2, v252
.LBB0_464:
	ds_write_b32 v14, v2 offset:7920
	s_and_b64 vcc, exec, s[4:5]
	s_waitcnt vmcnt(36)
	v_cndmask_b32_e64 v2, 0, v30, s[84:85]
	s_cbranch_vccnz .LBB0_283
	v_mul_f32_e32 v2, v2, v253
	s_branch .LBB0_283

; #define LAS __attribute__((address_space(3)))
; __device__ __forceinline__ void tr_load(const TrItem& t, float (&v)[32], int lane) {
;     const int n = lane & 31, kh = lane >> 5; const float* wp = t.W + (size_t)(t.k0 + kh) * t.ldw + t.n0 + (n < t.nvalid ? n : 0);
; #pragma unroll
;     for (int i = 0; i < 32; ++i) v[i] = wp[(size_t)(2 * i) * t.ldw];
; }
; __device__ __forceinline__ void tr_finish(const TrItem& t, const float (&v)[32], LAS float* scr, int lane) {
;     const int n = lane & 31, kh = lane >> 5;
; #pragma unroll
;     for (int i = 0; i < 32; ++i) { float x = n < t.nvalid ? v[i] : 0.f; if (t.g) x *= t.g[t.k0 + 2 * i + kh]; scr[(2 * i + kh) * 33 + n] = x; }
.LBB0_1027:
	v_add_u32_e32 v6, s56, v1
	v_ashrrev_i32_e32 v7, 31, v6
	v_mul_lo_u32 v2, s76, v7
	v_mul_lo_u32 v5, s77, v6
	s_waitcnt vmcnt(44)
	v_mad_u64_u32 v[46:47], s[0:1], s76, v6, 0
	v_add3_u32 v47, v47, v2, v5
	v_lshl_add_u64 v[46:47], v[46:47], 2, s[4:5]
	s_ashr_i32 s7, s6, 31
	v_cndmask_b32_e64 v2, 0, v0, s[80:81]
	v_lshl_add_u64 v[46:47], s[6:7], 2, v[46:47]
	v_lshlrev_b32_e32 v2, 2, v2
	v_lshl_add_u64 v[46:47], v[46:47], 0, v[2:3]
	s_lshl_b64 s[0:1], s[76:77], 3
	global_load_dword v77, v[46:47], off
	v_lshl_add_u64 v[46:47], v[46:47], 0, s[0:1]
	global_load_dword v76, v[46:47], off
	v_lshl_add_u64 v[46:47], v[46:47], 0, s[0:1]
	global_load_dword v75, v[46:47], off
	v_lshl_add_u64 v[46:47], v[46:47], 0, s[0:1]
	global_load_dword v74, v[46:47], off
	v_lshl_add_u64 v[46:47], v[46:47], 0, s[0:1]
	global_load_dword v73, v[46:47], off
	v_lshl_add_u64 v[46:47], v[46:47], 0, s[0:1]
	global_load_dword v72, v[46:47], off
	v_lshl_add_u64 v[46:47], v[46:47], 0, s[0:1]
	global_load_dword v70, v[46:47], off
	v_lshl_add_u64 v[46:47], v[46:47], 0, s[0:1]
	global_load_dword v71, v[46:47], off
	v_lshl_add_u64 v[46:47], v[46:47], 0, s[0:1]
	global_load_dword v69, v[46:47], off
	v_lshl_add_u64 v[46:47], v[46:47], 0, s[0:1]
	global_load_dword v68, v[46:47], off
	v_lshl_add_u64 v[46:47], v[46:47], 0, s[0:1]
	global_load_dword v67, v[46:47], off
	v_lshl_add_u64 v[46:47], v[46:47], 0, s[0:1]
	global_load_dword v66, v[46:47], off
	v_lshl_add_u64 v[46:47], v[46:47], 0, s[0:1]
	global_load_dword v65, v[46:47], off
	v_lshl_add_u64 v[46:47], v[46:47], 0, s[0:1]
	global_load_dword v64, v[46:47], off
	v_lshl_add_u64 v[46:47], v[46:47], 0, s[0:1]
	global_load_dword v63, v[46:47], off
	v_lshl_add_u64 v[46:47], v[46:47], 0, s[0:1]
	global_load_dword v62, v[46:47], off
	v_lshl_add_u64 v[46:47], v[46:47], 0, s[0:1]
	global_load_dword v61, v[46:47], off
	v_lshl_add_u64 v[46:47], v[46:47], 0, s[0:1]
	global_load_dword v59, v[46:47], off
	v_lshl_add_u64 v[46:47], v[46:47], 0, s[0:1]
	global_load_dword v57, v[46:47], off
	v_lshl_add_u64 v[46:47], v[46:47], 0, s[0:1]
	global_load_dword v55, v[46:47], off
	v_lshl_add_u64 v[46:47], v[46:47], 0, s[0:1]
	global_load_dword v53, v[46:47], off
	v_lshl_add_u64 v[46:47], v[46:47], 0, s[0:1]
	v_lshl_add_u64 v[78:79], v[46:47], 0, s[0:1]
	global_load_dword v50, v[46:47], off
	s_nop 0
	global_load_dword v47, v[78:79], off
	v_lshl_add_u64 v[78:79], v[78:79], 0, s[0:1]
	global_load_dword v46, v[78:79], off
	v_lshl_add_u64 v[78:79], v[78:79], 0, s[0:1]
	global_load_dword v44, v[78:79], off
	v_lshl_add_u64 v[78:79], v[78:79], 0, s[0:1]
	global_load_dword v42, v[78:79], off
	v_lshl_add_u64 v[78:79], v[78:79], 0, s[0:1]
	global_load_dword v40, v[78:79], off
	v_lshl_add_u64 v[78:79], v[78:79], 0, s[0:1]
	global_load_dword v38, v[78:79], off
	v_lshl_add_u64 v[78:79], v[78:79], 0, s[0:1]
	global_load_dword v36, v[78:79], off
	v_lshl_add_u64 v[78:79], v[78:79], 0, s[0:1]
	global_load_dword v34, v[78:79], off
	v_lshl_add_u64 v[78:79], v[78:79], 0, s[0:1]
	global_load_dword v32, v[78:79], off
	v_lshl_add_u64 v[78:79], v[78:79], 0, s[0:1]
	global_load_dword v30, v[78:79], off
	v_cmp_gt_u32_e64 s[4:5], s21, v0
	s_cmp_lg_u64 s[24:25], 0
	v_add_u32_e32 v8, s20, v1
	s_cselect_b64 s[0:1], -1, 0
	s_cmp_eq_u64 s[24:25], 0
	s_waitcnt vmcnt(62)
	v_cndmask_b32_e64 v2, 0, v9, s[4:5]
	v_ashrrev_i32_e32 v9, 31, v8
	s_cbranch_scc1 .LBB0_1029
	v_lshl_add_u64 v[78:79], v[8:9], 2, s[24:25]
	global_load_dword v238, v[78:79], off
	global_load_dword v239, v[78:79], off offset:8
	global_load_dword v240, v[78:79], off offset:16
	global_load_dword v241, v[78:79], off offset:24
	global_load_dword v242, v[78:79], off offset:32
	global_load_dword v243, v[78:79], off offset:40
	global_load_dword v244, v[78:79], off offset:48
	global_load_dword v245, v[78:79], off offset:56
	global_load_dword v246, v[78:79], off offset:64
	global_load_dword v247, v[78:79], off offset:72
	global_load_dword v248, v[78:79], off offset:80
	global_load_dword v249, v[78:79], off offset:88
	global_load_dword v250, v[78:79], off offset:96
	global_load_dword v251, v[78:79], off offset:104
	global_load_dword v252, v[78:79], off offset:112
	global_load_dword v253, v[78:79], off offset:120
	s_waitcnt vmcnt(0)
	v_mul_f32_e32 v2, v2, v238
.LBB0_1029:
	ds_write_b32 v14, v2
	v_cndmask_b32_e64 v2, 0, 1, s[0:1]
	v_cmp_ne_u32_e64 s[6:7], 1, v2
	s_andn2_b64 vcc, exec, s[0:1]
	v_cndmask_b32_e64 v2, 0, v60, s[4:5]
	s_cbranch_vccnz .LBB0_1031
	v_lshl_add_u64 v[78:79], v[8:9], 2, s[24:25]
	v_mul_f32_e32 v2, v2, v239
.LBB0_1031:
	ds_write_b32 v14, v2 offset:264
	s_and_b64 vcc, exec, s[6:7]
	s_waitcnt vmcnt(61)
	v_cndmask_b32_e64 v2, 0, v58, s[4:5]
	s_cbranch_vccnz .LBB0_1033
	v_lshl_add_u64 v[78:79], v[8:9], 2, s[24:25]
	v_mul_f32_e32 v2, v2, v240
.LBB0_1033:
	ds_write_b32 v14, v2 offset:528
	s_and_b64 vcc, exec, s[6:7]
	s_waitcnt vmcnt(60)
	v_cndmask_b32_e64 v2, 0, v56, s[4:5]
	s_cbranch_vccnz .LBB0_1035
	v_lshl_add_u64 v[78:79], v[8:9], 2, s[24:25]
	v_mul_f32_e32 v2, v2, v241
.LBB0_1035:
	ds_write_b32 v14, v2 offset:792
	s_and_b64 vcc, exec, s[6:7]
	s_waitcnt vmcnt(59)
	v_cndmask_b32_e64 v2, 0, v54, s[4:5]
	s_cbranch_vccnz .LBB0_1037
	v_lshl_add_u64 v[78:79], v[8:9], 2, s[24:25]
	v_mul_f32_e32 v2, v2, v242
.LBB0_1037:
	ds_write_b32 v14, v2 offset:1056
	s_and_b64 vcc, exec, s[6:7]
	s_waitcnt vmcnt(58)
	v_cndmask_b32_e64 v2, 0, v52, s[4:5]
	s_cbranch_vccnz .LBB0_1039
	v_lshl_add_u64 v[78:79], v[8:9], 2, s[24:25]
	v_mul_f32_e32 v2, v2, v243
.LBB0_1039:
	ds_write_b32 v14, v2 offset:1320
	s_and_b64 vcc, exec, s[6:7]
	s_waitcnt vmcnt(57)
	v_cndmask_b32_e64 v2, 0, v49, s[4:5]
	s_cbranch_vccnz .LBB0_1041
	v_lshl_add_u64 v[78:79], v[8:9], 2, s[24:25]
	v_mul_f32_e32 v2, v2, v244
; #define LAS __attribute__((address_space(3)))
; __device__ __forceinline__ void tr_finish(const TrItem& t, const float (&v)[32], LAS float* scr, int lane) {
;     const int n = lane & 31, kh = lane >> 5;
; #pragma unroll
;     for (int i = 0; i < 32; ++i) { float x = n < t.nvalid ? v[i] : 0.f; if (t.g) x *= t.g[t.k0 + 2 * i + kh]; scr[(2 * i + kh) * 33 + n] = x; }
.LBB0_1041:
	ds_write_b32 v14, v2 offset:1584
	s_and_b64 vcc, exec, s[6:7]
	s_waitcnt vmcnt(56)
	v_cndmask_b32_e64 v2, 0, v51, s[4:5]
	s_cbranch_vccnz .LBB0_1043
	v_lshl_add_u64 v[78:79], v[8:9], 2, s[24:25]
	v_mul_f32_e32 v2, v2, v245
.LBB0_1043:
	ds_write_b32 v14, v2 offset:1848
	s_and_b64 vcc, exec, s[6:7]
	s_waitcnt vmcnt(55)
	v_cndmask_b32_e64 v2, 0, v48, s[4:5]
	s_cbranch_vccnz .LBB0_1045
	v_lshl_add_u64 v[48:49], v[8:9], 2, s[24:25]
	v_mul_f32_e32 v2, v2, v246
.LBB0_1045:
	ds_write_b32 v14, v2 offset:2112
	s_and_b64 vcc, exec, s[6:7]
	s_waitcnt vmcnt(54)
	v_cndmask_b32_e64 v2, 0, v45, s[4:5]
	s_cbranch_vccnz .LBB0_1047
	v_lshl_add_u64 v[48:49], v[8:9], 2, s[24:25]
	v_mul_f32_e32 v2, v2, v247
.LBB0_1047:
	ds_write_b32 v14, v2 offset:2376
	s_and_b64 vcc, exec, s[6:7]
	s_waitcnt vmcnt(53)
	v_cndmask_b32_e64 v2, 0, v43, s[4:5]
	s_cbranch_vccnz .LBB0_1049
	v_lshl_add_u64 v[48:49], v[8:9], 2, s[24:25]
	v_mul_f32_e32 v2, v2, v248
.LBB0_1049:
	ds_write_b32 v14, v2 offset:2640
	s_and_b64 vcc, exec, s[6:7]
	s_waitcnt vmcnt(52)
	v_cndmask_b32_e64 v2, 0, v41, s[4:5]
	s_cbranch_vccnz .LBB0_1051
	v_lshl_add_u64 v[48:49], v[8:9], 2, s[24:25]
	v_mul_f32_e32 v2, v2, v249
.LBB0_1051:
	ds_write_b32 v14, v2 offset:2904
	s_and_b64 vcc, exec, s[6:7]
	s_waitcnt vmcnt(51)
	v_cndmask_b32_e64 v2, 0, v39, s[4:5]
	s_cbranch_vccnz .LBB0_1053
	v_lshl_add_u64 v[48:49], v[8:9], 2, s[24:25]
	v_mul_f32_e32 v2, v2, v250
.LBB0_1053:
	ds_write_b32 v14, v2 offset:3168
	s_and_b64 vcc, exec, s[6:7]
	s_waitcnt vmcnt(50)
	v_cndmask_b32_e64 v2, 0, v37, s[4:5]
	s_cbranch_vccnz .LBB0_1055
	v_lshl_add_u64 v[48:49], v[8:9], 2, s[24:25]
	v_mul_f32_e32 v2, v2, v251
.LBB0_1055:
	ds_write_b32 v14, v2 offset:3432
	s_and_b64 vcc, exec, s[6:7]
	s_waitcnt vmcnt(49)
	v_cndmask_b32_e64 v2, 0, v35, s[4:5]
	s_cbranch_vccnz .LBB0_1057
	v_lshl_add_u64 v[48:49], v[8:9], 2, s[24:25]
	v_mul_f32_e32 v2, v2, v252
.LBB0_1057:
	ds_write_b32 v14, v2 offset:3696
	s_and_b64 vcc, exec, s[6:7]
	s_waitcnt vmcnt(48)
	v_cndmask_b32_e64 v2, 0, v33, s[4:5]
	s_cbranch_vccnz .LBB0_1059
	v_lshl_add_u64 v[48:49], v[8:9], 2, s[24:25]
	v_mul_f32_e32 v2, v2, v253
.LBB0_1059:
	ds_write_b32 v14, v2 offset:3960
	s_and_b64 vcc, exec, s[6:7]
	s_waitcnt vmcnt(47)
	v_cndmask_b32_e64 v2, 0, v31, s[4:5]
	s_cbranch_vccnz .LBB0_1061
	v_lshl_add_u64 v[48:49], v[8:9], 2, s[24:25]
	global_load_dword v238, v[48:49], off offset:128
	global_load_dword v239, v[48:49], off offset:136
	global_load_dword v240, v[48:49], off offset:144
	global_load_dword v241, v[48:49], off offset:152
	global_load_dword v242, v[48:49], off offset:160
	global_load_dword v243, v[48:49], off offset:168
	global_load_dword v244, v[48:49], off offset:176
	global_load_dword v245, v[48:49], off offset:184
	global_load_dword v246, v[48:49], off offset:192
	global_load_dword v247, v[48:49], off offset:200
	global_load_dword v248, v[48:49], off offset:208
	global_load_dword v249, v[48:49], off offset:216
	global_load_dword v250, v[48:49], off offset:224
	global_load_dword v251, v[48:49], off offset:232
	global_load_dword v252, v[48:49], off offset:240
	global_load_dword v253, v[48:49], off offset:248
	s_waitcnt vmcnt(0)
	v_mul_f32_e32 v2, v2, v238
.LBB0_1061:
	ds_write_b32 v14, v2 offset:4224
	s_and_b64 vcc, exec, s[6:7]
	s_waitcnt vmcnt(46)
	v_cndmask_b32_e64 v2, 0, v29, s[4:5]
	s_cbranch_vccnz .LBB0_1063
	v_lshl_add_u64 v[48:49], v[8:9], 2, s[24:25]
	v_mul_f32_e32 v2, v2, v239
.LBB0_1063:
	ds_write_b32 v14, v2 offset:4488
	s_and_b64 vcc, exec, s[6:7]
	s_waitcnt vmcnt(45)
	v_cndmask_b32_e64 v2, 0, v28, s[4:5]
	s_cbranch_vccnz .LBB0_1065
	v_lshl_add_u64 v[28:29], v[8:9], 2, s[24:25]
	v_mul_f32_e32 v2, v2, v240
.LBB0_1065:
	ds_write_b32 v14, v2 offset:4752
	s_and_b64 vcc, exec, s[6:7]
	s_waitcnt vmcnt(44)
	v_cndmask_b32_e64 v2, 0, v27, s[4:5]
	s_cbranch_vccnz .LBB0_1067
	v_lshl_add_u64 v[28:29], v[8:9], 2, s[24:25]
	v_mul_f32_e32 v2, v2, v241
.LBB0_1067:
	ds_write_b32 v14, v2 offset:5016
	s_and_b64 vcc, exec, s[6:7]
	s_waitcnt vmcnt(43)
	v_cndmask_b32_e64 v2, 0, v26, s[4:5]
	s_cbranch_vccnz .LBB0_1069
	v_lshl_add_u64 v[26:27], v[8:9], 2, s[24:25]
	v_mul_f32_e32 v2, v2, v242
.LBB0_1069:
	ds_write_b32 v14, v2 offset:5280
	s_and_b64 vcc, exec, s[6:7]
	s_waitcnt vmcnt(42)
	v_cndmask_b32_e64 v2, 0, v25, s[4:5]
	s_cbranch_vccnz .LBB0_1071
	v_lshl_add_u64 v[26:27], v[8:9], 2, s[24:25]
	v_mul_f32_e32 v2, v2, v243
.LBB0_1071:
	ds_write_b32 v14, v2 offset:5544
	s_and_b64 vcc, exec, s[6:7]
	s_waitcnt vmcnt(41)
	v_cndmask_b32_e64 v2, 0, v24, s[4:5]
	s_cbranch_vccnz .LBB0_1073
	v_lshl_add_u64 v[24:25], v[8:9], 2, s[24:25]
	v_mul_f32_e32 v2, v2, v244
.LBB0_1073:
	ds_write_b32 v14, v2 offset:5808
	s_and_b64 vcc, exec, s[6:7]
	s_waitcnt vmcnt(40)
	v_cndmask_b32_e64 v2, 0, v23, s[4:5]
	s_cbranch_vccnz .LBB0_1075
	v_lshl_add_u64 v[24:25], v[8:9], 2, s[24:25]
	v_mul_f32_e32 v2, v2, v245
.LBB0_1075:
	ds_write_b32 v14, v2 offset:6072
	s_and_b64 vcc, exec, s[6:7]
	s_waitcnt vmcnt(39)
	v_cndmask_b32_e64 v2, 0, v22, s[4:5]
	s_cbranch_vccnz .LBB0_1077
	v_lshl_add_u64 v[22:23], v[8:9], 2, s[24:25]
	v_mul_f32_e32 v2, v2, v246
.LBB0_1077:
	ds_write_b32 v14, v2 offset:6336
	s_and_b64 vcc, exec, s[6:7]
	s_waitcnt vmcnt(38)
	v_cndmask_b32_e64 v2, 0, v21, s[4:5]
	s_cbranch_vccnz .LBB0_1079
	v_lshl_add_u64 v[22:23], v[8:9], 2, s[24:25]
	v_mul_f32_e32 v2, v2, v247
.LBB0_1079:
	ds_write_b32 v14, v2 offset:6600
	s_and_b64 vcc, exec, s[6:7]
	s_waitcnt vmcnt(37)
	v_cndmask_b32_e64 v2, 0, v20, s[4:5]
	s_cbranch_vccnz .LBB0_1081
	v_lshl_add_u64 v[20:21], v[8:9], 2, s[24:25]
	v_mul_f32_e32 v2, v2, v248
.LBB0_1081:
	ds_write_b32 v14, v2 offset:6864
	s_and_b64 vcc, exec, s[6:7]
	s_waitcnt vmcnt(36)
	v_cndmask_b32_e64 v2, 0, v19, s[4:5]
	s_cbranch_vccnz .LBB0_1083
	v_lshl_add_u64 v[20:21], v[8:9], 2, s[24:25]
	v_mul_f32_e32 v2, v2, v249
.LBB0_1083:
	ds_write_b32 v14, v2 offset:7128
	s_and_b64 vcc, exec, s[6:7]
	s_waitcnt vmcnt(35)
	v_cndmask_b32_e64 v2, 0, v18, s[4:5]
	s_cbranch_vccnz .LBB0_1085
	v_lshl_add_u64 v[18:19], v[8:9], 2, s[24:25]
	v_mul_f32_e32 v2, v2, v250
.LBB0_1085:
	ds_write_b32 v14, v2 offset:7392
	s_and_b64 vcc, exec, s[6:7]
	s_waitcnt vmcnt(34)
	v_cndmask_b32_e64 v2, 0, v17, s[4:5]
	s_cbranch_vccnz .LBB0_1087
	v_lshl_add_u64 v[18:19], v[8:9], 2, s[24:25]
	v_mul_f32_e32 v2, v2, v251
.LBB0_1087:
	ds_write_b32 v14, v2 offset:7656
	s_and_b64 vcc, exec, s[6:7]
	s_waitcnt vmcnt(33)
	v_cndmask_b32_e64 v2, 0, v16, s[4:5]
	s_cbranch_vccnz .LBB0_1089
	v_lshl_add_u64 v[16:17], v[8:9], 2, s[24:25]
	v_mul_f32_e32 v2, v2, v252
.LBB0_1089:
	ds_write_b32 v14, v2 offset:7920
	s_and_b64 vcc, exec, s[6:7]
	s_waitcnt vmcnt(32)
	v_cndmask_b32_e64 v2, 0, v15, s[4:5]
	s_cbranch_vccnz .LBB0_1091
	v_lshl_add_u64 v[8:9], v[8:9], 2, s[24:25]
	v_mul_f32_e32 v2, v2, v253

; #define LAS __attribute__((address_space(3)))
; __device__ __forceinline__ void tr_load(const TrItem& t, float (&v)[32], int lane) {
;     const int n = lane & 31, kh = lane >> 5; const float* wp = t.W + (size_t)(t.k0 + kh) * t.ldw + t.n0 + (n < t.nvalid ? n : 0);
; #pragma unroll
;     for (int i = 0; i < 32; ++i) v[i] = wp[(size_t)(2 * i) * t.ldw];
; }
; __device__ __forceinline__ void tr_finish(const TrItem& t, const float (&v)[32], LAS float* scr, int lane) {
;     const int n = lane & 31, kh = lane >> 5;
; #pragma unroll
;     for (int i = 0; i < 32; ++i) { float x = n < t.nvalid ? v[i] : 0.f; if (t.g) x *= t.g[t.k0 + 2 * i + kh]; scr[(2 * i + kh) * 33 + n] = x; }
.LBB0_1117:
	v_add_u32_e32 v2, s20, v1
	v_ashrrev_i32_e32 v5, 31, v2
	v_mul_lo_u32 v5, s76, v5
	v_mul_lo_u32 v15, s77, v2
	v_mad_u64_u32 v[8:9], s[0:1], s76, v2, 0
	v_add3_u32 v9, v9, v5, v15
	v_cmp_gt_u32_e32 vcc, s21, v0
	v_lshl_add_u64 v[8:9], v[8:9], 2, s[4:5]
	s_ashr_i32 s7, s6, 31
	v_cndmask_b32_e32 v2, 0, v0, vcc
	v_lshl_add_u64 v[8:9], s[6:7], 2, v[8:9]
	v_lshlrev_b32_e32 v2, 2, v2
	v_lshl_add_u64 v[16:17], v[8:9], 0, v[2:3]
	s_lshl_b64 s[0:1], s[76:77], 3
	global_load_dword v9, v[16:17], off
	v_lshl_add_u64 v[16:17], v[16:17], 0, s[0:1]
	global_load_dword v60, v[16:17], off
	v_lshl_add_u64 v[16:17], v[16:17], 0, s[0:1]
	global_load_dword v58, v[16:17], off
	v_lshl_add_u64 v[16:17], v[16:17], 0, s[0:1]
	global_load_dword v56, v[16:17], off
	v_lshl_add_u64 v[16:17], v[16:17], 0, s[0:1]
	global_load_dword v54, v[16:17], off
	v_lshl_add_u64 v[16:17], v[16:17], 0, s[0:1]
	global_load_dword v52, v[16:17], off
	v_lshl_add_u64 v[16:17], v[16:17], 0, s[0:1]
	global_load_dword v49, v[16:17], off
	v_lshl_add_u64 v[16:17], v[16:17], 0, s[0:1]
	global_load_dword v51, v[16:17], off
	v_lshl_add_u64 v[16:17], v[16:17], 0, s[0:1]
	global_load_dword v48, v[16:17], off
	v_lshl_add_u64 v[16:17], v[16:17], 0, s[0:1]
	global_load_dword v45, v[16:17], off
	v_lshl_add_u64 v[16:17], v[16:17], 0, s[0:1]
	global_load_dword v43, v[16:17], off
	v_lshl_add_u64 v[16:17], v[16:17], 0, s[0:1]
	global_load_dword v41, v[16:17], off
	v_lshl_add_u64 v[16:17], v[16:17], 0, s[0:1]
	global_load_dword v39, v[16:17], off
	v_lshl_add_u64 v[16:17], v[16:17], 0, s[0:1]
	global_load_dword v37, v[16:17], off
	v_lshl_add_u64 v[16:17], v[16:17], 0, s[0:1]
	global_load_dword v35, v[16:17], off
	v_lshl_add_u64 v[16:17], v[16:17], 0, s[0:1]
	global_load_dword v33, v[16:17], off
	v_lshl_add_u64 v[16:17], v[16:17], 0, s[0:1]
	global_load_dword v31, v[16:17], off
	v_lshl_add_u64 v[16:17], v[16:17], 0, s[0:1]
	global_load_dword v29, v[16:17], off
	v_lshl_add_u64 v[16:17], v[16:17], 0, s[0:1]
	global_load_dword v28, v[16:17], off
	v_lshl_add_u64 v[16:17], v[16:17], 0, s[0:1]
	global_load_dword v27, v[16:17], off
	v_lshl_add_u64 v[16:17], v[16:17], 0, s[0:1]
	global_load_dword v26, v[16:17], off
	v_lshl_add_u64 v[16:17], v[16:17], 0, s[0:1]
	global_load_dword v25, v[16:17], off
	v_lshl_add_u64 v[16:17], v[16:17], 0, s[0:1]
	global_load_dword v24, v[16:17], off
	v_lshl_add_u64 v[16:17], v[16:17], 0, s[0:1]
	global_load_dword v23, v[16:17], off
	v_lshl_add_u64 v[16:17], v[16:17], 0, s[0:1]
	global_load_dword v22, v[16:17], off
	v_lshl_add_u64 v[16:17], v[16:17], 0, s[0:1]
	global_load_dword v21, v[16:17], off
	v_lshl_add_u64 v[16:17], v[16:17], 0, s[0:1]
	global_load_dword v20, v[16:17], off
	v_lshl_add_u64 v[16:17], v[16:17], 0, s[0:1]
	global_load_dword v19, v[16:17], off
	v_lshl_add_u64 v[16:17], v[16:17], 0, s[0:1]
	v_lshl_add_u64 v[78:79], v[16:17], 0, s[0:1]
	global_load_dword v18, v[16:17], off
	s_nop 0
	global_load_dword v17, v[78:79], off
	v_lshl_add_u64 v[78:79], v[78:79], 0, s[0:1]
	global_load_dword v16, v[78:79], off
	v_lshl_add_u64 v[78:79], v[78:79], 0, s[0:1]
	global_load_dword v15, v[78:79], off
	s_andn2_b64 vcc, exec, s[84:85]
	s_cbranch_vccnz .LBB0_1000
	s_cmp_lg_u64 s[86:87], 0
	s_cselect_b64 s[0:1], -1, 0
	s_cmp_eq_u64 s[86:87], 0
	s_waitcnt vmcnt(62)
	v_cndmask_b32_e64 v2, 0, v77, s[80:81]
	v_lshl_add_u64 v[6:7], v[6:7], 2, s[86:87]
	s_cbranch_scc1 .LBB0_1120
	global_load_dword v238, v[6:7], off
	global_load_dword v239, v[6:7], off offset:8
	global_load_dword v240, v[6:7], off offset:16
	global_load_dword v241, v[6:7], off offset:24
	global_load_dword v242, v[6:7], off offset:32
	global_load_dword v243, v[6:7], off offset:40
	global_load_dword v244, v[6:7], off offset:48
	global_load_dword v245, v[6:7], off offset:56
	global_load_dword v246, v[6:7], off offset:64
	global_load_dword v247, v[6:7], off offset:72
	global_load_dword v248, v[6:7], off offset:80
	global_load_dword v249, v[6:7], off offset:88
	global_load_dword v250, v[6:7], off offset:96
	global_load_dword v251, v[6:7], off offset:104
	global_load_dword v252, v[6:7], off offset:112
	global_load_dword v253, v[6:7], off offset:120
	s_waitcnt vmcnt(0)
	v_mul_f32_e32 v2, v2, v238
.LBB0_1120:
	ds_write_b32 v14, v2
	v_cndmask_b32_e64 v2, 0, 1, s[0:1]
	v_cmp_ne_u32_e64 s[4:5], 1, v2
	s_andn2_b64 vcc, exec, s[0:1]
	v_cndmask_b32_e64 v2, 0, v76, s[80:81]
	s_cbranch_vccnz .LBB0_1122
	v_mul_f32_e32 v2, v2, v239
.LBB0_1122:
	ds_write_b32 v14, v2 offset:264
	s_and_b64 vcc, exec, s[4:5]
	v_cndmask_b32_e64 v2, 0, v75, s[80:81]
	s_cbranch_vccnz .LBB0_1124
	v_mul_f32_e32 v2, v2, v240
.LBB0_1124:
	ds_write_b32 v14, v2 offset:528
	s_and_b64 vcc, exec, s[4:5]
	v_cndmask_b32_e64 v2, 0, v74, s[80:81]
	s_cbranch_vccnz .LBB0_1126
	v_mul_f32_e32 v2, v2, v241
.LBB0_1126:
	ds_write_b32 v14, v2 offset:792
	s_and_b64 vcc, exec, s[4:5]
	v_cndmask_b32_e64 v2, 0, v73, s[80:81]
	s_cbranch_vccnz .LBB0_1128
	v_mul_f32_e32 v2, v2, v242
.LBB0_1128:
	ds_write_b32 v14, v2 offset:1056
	s_and_b64 vcc, exec, s[4:5]
	v_cndmask_b32_e64 v2, 0, v72, s[80:81]
	s_cbranch_vccnz .LBB0_1130
	v_mul_f32_e32 v2, v2, v243
.LBB0_1130:
	ds_write_b32 v14, v2 offset:1320
	s_and_b64 vcc, exec, s[4:5]
	s_waitcnt vmcnt(61)
	v_cndmask_b32_e64 v2, 0, v70, s[80:81]
	s_cbranch_vccnz .LBB0_1132
	v_mul_f32_e32 v2, v2, v244
.LBB0_1132:
	ds_write_b32 v14, v2 offset:1584
	s_and_b64 vcc, exec, s[4:5]
	s_waitcnt vmcnt(60)
	v_cndmask_b32_e64 v2, 0, v71, s[80:81]
	s_cbranch_vccnz .LBB0_1134
	v_mul_f32_e32 v2, v2, v245
; #define LAS __attribute__((address_space(3)))
; __device__ __forceinline__ void tr_finish(const TrItem& t, const float (&v)[32], LAS float* scr, int lane) {
;     const int n = lane & 31, kh = lane >> 5;
; #pragma unroll
;     for (int i = 0; i < 32; ++i) { float x = n < t.nvalid ? v[i] : 0.f; if (t.g) x *= t.g[t.k0 + 2 * i + kh]; scr[(2 * i + kh) * 33 + n] = x; }
.LBB0_1134:
	ds_write_b32 v14, v2 offset:1848
	s_and_b64 vcc, exec, s[4:5]
	s_waitcnt vmcnt(59)
	v_cndmask_b32_e64 v2, 0, v69, s[80:81]
	s_cbranch_vccnz .LBB0_1136
	v_mul_f32_e32 v2, v2, v246
.LBB0_1136:
	ds_write_b32 v14, v2 offset:2112
	s_and_b64 vcc, exec, s[4:5]
	s_waitcnt vmcnt(58)
	v_cndmask_b32_e64 v2, 0, v68, s[80:81]
	s_cbranch_vccnz .LBB0_1138
	v_mul_f32_e32 v2, v2, v247
.LBB0_1138:
	ds_write_b32 v14, v2 offset:2376
	s_and_b64 vcc, exec, s[4:5]
	s_waitcnt vmcnt(57)
	v_cndmask_b32_e64 v2, 0, v67, s[80:81]
	s_cbranch_vccnz .LBB0_1140
	v_mul_f32_e32 v2, v2, v248
.LBB0_1140:
	ds_write_b32 v14, v2 offset:2640
	s_and_b64 vcc, exec, s[4:5]
	s_waitcnt vmcnt(56)
	v_cndmask_b32_e64 v2, 0, v66, s[80:81]
	s_cbranch_vccnz .LBB0_1142
	v_mul_f32_e32 v2, v2, v249
.LBB0_1142:
	ds_write_b32 v14, v2 offset:2904
	s_and_b64 vcc, exec, s[4:5]
	s_waitcnt vmcnt(55)
	v_cndmask_b32_e64 v2, 0, v65, s[80:81]
	s_cbranch_vccnz .LBB0_1144
	v_mul_f32_e32 v2, v2, v250
.LBB0_1144:
	ds_write_b32 v14, v2 offset:3168
	s_and_b64 vcc, exec, s[4:5]
	s_waitcnt vmcnt(54)
	v_cndmask_b32_e64 v2, 0, v64, s[80:81]
	s_cbranch_vccnz .LBB0_1146
	v_mul_f32_e32 v2, v2, v251
.LBB0_1146:
	ds_write_b32 v14, v2 offset:3432
	s_and_b64 vcc, exec, s[4:5]
	s_waitcnt vmcnt(53)
	v_cndmask_b32_e64 v2, 0, v63, s[80:81]
	s_cbranch_vccnz .LBB0_1148
	v_mul_f32_e32 v2, v2, v252
.LBB0_1148:
	ds_write_b32 v14, v2 offset:3696
	s_and_b64 vcc, exec, s[4:5]
	s_waitcnt vmcnt(52)
	v_cndmask_b32_e64 v2, 0, v62, s[80:81]
	s_cbranch_vccnz .LBB0_1150
	v_mul_f32_e32 v2, v2, v253
.LBB0_1150:
	ds_write_b32 v14, v2 offset:3960
	s_and_b64 vcc, exec, s[4:5]
	s_waitcnt vmcnt(51)
	v_cndmask_b32_e64 v2, 0, v61, s[80:81]
	s_cbranch_vccnz .LBB0_1152
	global_load_dword v238, v[6:7], off offset:128
	global_load_dword v239, v[6:7], off offset:136
	global_load_dword v240, v[6:7], off offset:144
	global_load_dword v241, v[6:7], off offset:152
	global_load_dword v242, v[6:7], off offset:160
	global_load_dword v243, v[6:7], off offset:168
	global_load_dword v244, v[6:7], off offset:176
	global_load_dword v245, v[6:7], off offset:184
	global_load_dword v246, v[6:7], off offset:192
	global_load_dword v247, v[6:7], off offset:200
	global_load_dword v248, v[6:7], off offset:208
	global_load_dword v249, v[6:7], off offset:216
	global_load_dword v250, v[6:7], off offset:224
	global_load_dword v251, v[6:7], off offset:232
	global_load_dword v252, v[6:7], off offset:240
	global_load_dword v253, v[6:7], off offset:248
	s_waitcnt vmcnt(0)
	v_mul_f32_e32 v2, v2, v238
.LBB0_1152:
	ds_write_b32 v14, v2 offset:4224
	s_and_b64 vcc, exec, s[4:5]
	s_waitcnt vmcnt(50)
	v_cndmask_b32_e64 v2, 0, v59, s[80:81]
	s_cbranch_vccnz .LBB0_1154
	v_mul_f32_e32 v2, v2, v239
.LBB0_1154:
	ds_write_b32 v14, v2 offset:4488
	s_and_b64 vcc, exec, s[4:5]
	s_waitcnt vmcnt(49)
	v_cndmask_b32_e64 v2, 0, v57, s[80:81]
	s_cbranch_vccnz .LBB0_1156
	v_mul_f32_e32 v2, v2, v240
.LBB0_1156:
	ds_write_b32 v14, v2 offset:4752
	s_and_b64 vcc, exec, s[4:5]
	s_waitcnt vmcnt(48)
	v_cndmask_b32_e64 v2, 0, v55, s[80:81]
	s_cbranch_vccnz .LBB0_1158
	v_mul_f32_e32 v2, v2, v241
.LBB0_1158:
	ds_write_b32 v14, v2 offset:5016
	s_and_b64 vcc, exec, s[4:5]
	s_waitcnt vmcnt(47)
	v_cndmask_b32_e64 v2, 0, v53, s[80:81]
	s_cbranch_vccnz .LBB0_1160
	v_mul_f32_e32 v2, v2, v242
.LBB0_1160:
	ds_write_b32 v14, v2 offset:5280
	s_and_b64 vcc, exec, s[4:5]
	s_waitcnt vmcnt(46)
	v_cndmask_b32_e64 v2, 0, v50, s[80:81]
	s_cbranch_vccnz .LBB0_1162
	v_mul_f32_e32 v2, v2, v243
.LBB0_1162:
	ds_write_b32 v14, v2 offset:5544
	s_and_b64 vcc, exec, s[4:5]
	s_waitcnt vmcnt(45)
	v_cndmask_b32_e64 v2, 0, v47, s[80:81]
	s_cbranch_vccnz .LBB0_1164
	v_mul_f32_e32 v2, v2, v244
.LBB0_1164:
	ds_write_b32 v14, v2 offset:5808
	s_and_b64 vcc, exec, s[4:5]
	s_waitcnt vmcnt(44)
	v_cndmask_b32_e64 v2, 0, v46, s[80:81]
	s_cbranch_vccnz .LBB0_1166
	v_mul_f32_e32 v2, v2, v245
.LBB0_1166:
	ds_write_b32 v14, v2 offset:6072
	s_and_b64 vcc, exec, s[4:5]
	s_waitcnt vmcnt(43)
	v_cndmask_b32_e64 v2, 0, v44, s[80:81]
	s_cbranch_vccnz .LBB0_1168
	v_mul_f32_e32 v2, v2, v246
.LBB0_1168:
	ds_write_b32 v14, v2 offset:6336
	s_and_b64 vcc, exec, s[4:5]
	s_waitcnt vmcnt(42)
	v_cndmask_b32_e64 v2, 0, v42, s[80:81]
	s_cbranch_vccnz .LBB0_1170
	v_mul_f32_e32 v2, v2, v247
.LBB0_1170:
	ds_write_b32 v14, v2 offset:6600
	s_and_b64 vcc, exec, s[4:5]
	s_waitcnt vmcnt(41)
	v_cndmask_b32_e64 v2, 0, v40, s[80:81]
	s_cbranch_vccnz .LBB0_1172
	v_mul_f32_e32 v2, v2, v248
.LBB0_1172:
	ds_write_b32 v14, v2 offset:6864
	s_and_b64 vcc, exec, s[4:5]
	s_waitcnt vmcnt(40)
	v_cndmask_b32_e64 v2, 0, v38, s[80:81]
	s_cbranch_vccnz .LBB0_1174
	v_mul_f32_e32 v2, v2, v249
.LBB0_1174:
	ds_write_b32 v14, v2 offset:7128
	s_and_b64 vcc, exec, s[4:5]
	s_waitcnt vmcnt(39)
	v_cndmask_b32_e64 v2, 0, v36, s[80:81]
	s_cbranch_vccnz .LBB0_1176
	v_mul_f32_e32 v2, v2, v250
.LBB0_1176:
	ds_write_b32 v14, v2 offset:7392
	s_and_b64 vcc, exec, s[4:5]
	s_waitcnt vmcnt(38)
	v_cndmask_b32_e64 v2, 0, v34, s[80:81]
	s_cbranch_vccnz .LBB0_1178
	v_mul_f32_e32 v2, v2, v251
.LBB0_1178:
	ds_write_b32 v14, v2 offset:7656
	s_and_b64 vcc, exec, s[4:5]
	s_waitcnt vmcnt(37)
	v_cndmask_b32_e64 v2, 0, v32, s[80:81]
	s_cbranch_vccnz .LBB0_1180
	v_mul_f32_e32 v2, v2, v252
.LBB0_1180:
	ds_write_b32 v14, v2 offset:7920
	s_and_b64 vcc, exec, s[4:5]
	s_waitcnt vmcnt(36)
	v_cndmask_b32_e64 v2, 0, v30, s[80:81]
	s_cbranch_vccnz .LBB0_999
	v_mul_f32_e32 v2, v2, v253
	s_branch .LBB0_999
